# only the grid.sync removal and the GQA prefetch-wait ladder fix (no cache-policy changes)
# speedup vs baseline: 1.0032x; 1.0032x over previous
; __global__ void __launch_bounds__(512) mega(Args a) {
;     ...
;   const XcdBarrier xb = xcd_barrier_post((unsigned*)(a.ws + WS_BAR), xst);
;   if (a.ph_hi - a.ph_lo > 1) grid.sync();
;   const int wave_s = __builtin_amdgcn_readfirstlane((int)threadIdx.x >> 6);
;   if ((PHMASK & 1) && a.ph_lo == 0) {
.LBB0_5:
	s_or_b64 exec, exec, s[6:7]
	s_load_dwordx16 s[80:95], s[0:1], 0x0
.LBB0_17:
	v_readfirstlane_b32 s15, v1
	s_andn2_b32 s15, s15, 63
	s_cmp_lg_u32 s76, 0
	s_mov_b32 s0, 0
	s_cbranch_scc0 .LBB0_19
	s_cmp_le_i32 s77, s76
	s_cbranch_scc0 .LBB0_23
	s_branch .LBB0_389

; #define SWRITE(b, i) do { *(bf16x8*)(V_lds + (b) * SHM_V + vst0) = sr_[i].vs0;          \
;     *(bf16x8*)(V_lds + (b) * SHM_V + vst1) = sr_[i].vs1; int kc = sc * 2;               \
;     *(bf16x8*)(K_lds + (b) * SHM_K + KSWZ(sr, kc)) = sr_[i].ks0;                       \
;     *(bf16x8*)(K_lds + (b) * SHM_K + KSWZ(32 + sr, kc)) = sr_[i].ks1; } while (0)
; #define SWAIT() do { if constexpr (SDEPTH == 2) asm volatile("s_waitcnt vmcnt(4)" ::: "memory"); else asm volatile("s_waitcnt vmcnt(0)" ::: "memory"); } while (0)
; #define RESC(a) do { if (__any((a) < 1.f)) { if (hi == 0) al_l[r32] = (a); asm volatile("s_waitcnt lgkmcnt(0)" ::: "memory"); \
;     _Pragma("unroll") for (int d = 0; d < 4; ++d) _Pragma("unroll") for (int r = 0; r < 16; ++r) o[d][r] *= al_l[crow(r, hi)]; } } while (0)
; __device__ __forceinline__ void partialSM(f32x16& p0, f32x16& p1, float& m_reg, float& mn, float& alpha) {
;   constexpr float C = SCALE * 1.4426950408889634f;
;   float pmax = p0[0];
; #pragma unroll
;   for (int r = 1; r < 16; ++r) pmax = fmaxf(pmax, p0[r]);
; #pragma unroll
;   for (int r = 0; r < 16; ++r) pmax = fmaxf(pmax, p1[r]);
;   { auto rr = __builtin_amdgcn_permlane32_swap(__float_as_uint(pmax), __float_as_uint(pmax), false, false);
;     pmax = fmaxf(__uint_as_float(rr[0]), __uint_as_float(rr[1])); }
;   if (__builtin_expect(__all(pmax - m_reg <= THR / SCALE), 1)) { mn = m_reg; alpha = 1.f; }
;   else { mn = fmaxf(m_reg, pmax); alpha = __builtin_amdgcn_exp2f((m_reg - mn) * C); m_reg = mn; }
; template <int MODE, int SDEPTH, bool SIMPLE>
; __device__ __forceinline__ void attn_body(const Unit& U, char* lds, const int tid) {
;     ...
;     pv_d0(o, vb0 + (int)SHM_V, pa0, pa1, pa2, pa3); partialSM(pA0, pA1, m_reg, mnA, alA);
;     __syncthreads(); SWAIT(); SWRITE(1, SO);
;     RESC(alA); __syncthreads();
.LBB0_205:
	ds_read_b64_tr_b16 v[220:221], v188 offset:0
	ds_read_b64_tr_b16 v[222:223], v188 offset:0x800
	ds_read_b64_tr_b16 v[234:235], v188 offset:0x1000
	ds_read_b64_tr_b16 v[236:237], v188 offset:0x1800
	ds_read_b64_tr_b16 v[238:239], v188 offset:0x2000
	ds_read_b64_tr_b16 v[240:241], v188 offset:0x2800
	ds_read_b64_tr_b16 v[242:243], v188 offset:0x3000
	ds_read_b64_tr_b16 v[244:245], v188 offset:0x3800
	s_waitcnt lgkmcnt(0)
	s_nop 0
	v_mfma_f32_32x32x16_bf16 v[0:15], v[160:163], v[220:223], v[0:15]
	ds_read_b64_tr_b16 v[220:221], v188 offset:0x200
	ds_read_b64_tr_b16 v[222:223], v188 offset:0xa00
	v_mfma_f32_32x32x16_bf16 v[0:15], v[164:167], v[234:237], v[0:15]
	ds_read_b64_tr_b16 v[234:235], v188 offset:0x1200
	ds_read_b64_tr_b16 v[236:237], v188 offset:0x1a00
	v_mfma_f32_32x32x16_bf16 v[0:15], v[168:171], v[238:241], v[0:15]
	ds_read_b64_tr_b16 v[238:239], v188 offset:0x2200
	ds_read_b64_tr_b16 v[240:241], v188 offset:0x2a00
	v_mfma_f32_32x32x16_bf16 v[0:15], v[172:175], v[242:245], v[0:15]
	ds_read_b64_tr_b16 v[242:243], v188 offset:0x3200
	ds_read_b64_tr_b16 v[244:245], v188 offset:0x3a00
	s_waitcnt lgkmcnt(0)
	v_mfma_f32_32x32x16_bf16 v[48:63], v[160:163], v[220:223], v[48:63]
	ds_read_b64_tr_b16 v[220:221], v188 offset:0x400
	ds_read_b64_tr_b16 v[222:223], v188 offset:0xc00
	v_mfma_f32_32x32x16_bf16 v[48:63], v[164:167], v[234:237], v[48:63]
	ds_read_b64_tr_b16 v[234:235], v188 offset:0x1400
	ds_read_b64_tr_b16 v[236:237], v188 offset:0x1c00
	v_mfma_f32_32x32x16_bf16 v[48:63], v[168:171], v[238:241], v[48:63]
	ds_read_b64_tr_b16 v[238:239], v188 offset:0x2400
	ds_read_b64_tr_b16 v[240:241], v188 offset:0x2c00
	v_mfma_f32_32x32x16_bf16 v[48:63], v[172:175], v[242:245], v[48:63]
	ds_read_b64_tr_b16 v[242:243], v188 offset:0x3400
	ds_read_b64_tr_b16 v[244:245], v188 offset:0x3c00
	s_waitcnt lgkmcnt(0)
	v_mfma_f32_32x32x16_bf16 v[32:47], v[160:163], v[220:223], v[32:47]
	ds_read_b64_tr_b16 v[220:221], v188 offset:0x600
	ds_read_b64_tr_b16 v[222:223], v188 offset:0xe00
	v_mfma_f32_32x32x16_bf16 v[32:47], v[164:167], v[234:237], v[32:47]
	ds_read_b64_tr_b16 v[234:235], v188 offset:0x1600
	ds_read_b64_tr_b16 v[236:237], v188 offset:0x1e00
	v_mfma_f32_32x32x16_bf16 v[32:47], v[168:171], v[238:241], v[32:47]
	ds_read_b64_tr_b16 v[238:239], v188 offset:0x2600
	ds_read_b64_tr_b16 v[240:241], v188 offset:0x2e00
	v_mfma_f32_32x32x16_bf16 v[32:47], v[172:175], v[242:245], v[32:47]
	ds_read_b64_tr_b16 v[242:243], v188 offset:0x3600
	ds_read_b64_tr_b16 v[244:245], v188 offset:0x3e00
	s_waitcnt lgkmcnt(0)
	v_mfma_f32_32x32x16_bf16 v[16:31], v[160:163], v[220:223], v[16:31]
	v_max_f32_e32 v160, v81, v81
	v_max_f32_e32 v161, v80, v80
	v_max_f32_e32 v160, v161, v160
	v_max3_f32 v160, v160, v82, v83
	v_max3_f32 v160, v160, v84, v85
	v_max3_f32 v160, v160, v86, v87
	v_max3_f32 v160, v160, v88, v89
	v_max3_f32 v160, v160, v90, v91
	v_max3_f32 v160, v160, v92, v93
	v_mfma_f32_32x32x16_bf16 v[16:31], v[164:167], v[234:237], v[16:31]
	v_max3_f32 v160, v160, v94, v95
	v_max3_f32 v160, v160, v64, v65
	v_max3_f32 v160, v160, v66, v67
	v_max3_f32 v160, v160, v68, v69
	v_max3_f32 v160, v160, v70, v71
	v_max3_f32 v160, v160, v72, v73
	v_max3_f32 v160, v160, v74, v75
	v_max3_f32 v160, v160, v76, v77
	v_mfma_f32_32x32x16_bf16 v[16:31], v[168:171], v[238:241], v[16:31]
	v_max3_f32 v160, v160, v78, v79
	v_mov_b32_e32 v161, v160
	s_nop 1
	v_permlane32_swap_b32_e32 v160, v161
	v_max_f32_e32 v161, v161, v161
	v_max_f32_e32 v160, v160, v160
	v_max_f32_e32 v160, v160, v161
	v_sub_f32_e32 v161, v160, v216
	v_cmp_ge_f32_e32 vcc, s18, v161
	v_max_f32_e32 v161, v216, v216
	v_max_f32_e32 v161, v161, v160
	v_mfma_f32_32x32x16_bf16 v[16:31], v[172:175], v[242:245], v[16:31]
	v_sub_f32_e32 v160, v216, v161
	v_mul_f32_e32 v160, 0x3e0293ee, v160
	v_exp_f32_e32 v160, v160
	s_cmp_eq_u64 vcc, exec
	s_cselect_b64 s[0:1], -1, 0
	s_barrier
	s_waitcnt vmcnt(4)
	v_cndmask_b32_e64 v160, v160, 1.0, s[0:1]
	v_cmp_gt_f32_e32 vcc, 1.0, v160
	ds_write_b128 v191, v[144:147] offset:16384
	ds_write_b128 v202, v[148:151] offset:16384
	ds_write_b128 v190, v[152:155] offset:49152
	ds_write_b128 v203, v[156:159] offset:49152
	s_cbranch_vccz .LBB0_209
	s_and_saveexec_b64 s[42:43], s[36:37]
	ds_write_b32 v186, v160 offset:128
	s_or_b64 exec, exec, s[42:43]
	s_waitcnt lgkmcnt(0)
	v_add_u32_e32 v156, v185, v192
	ds_read_b128 v[144:147], v156 offset:224
	ds_read_b128 v[148:151], v156 offset:192
	ds_read_b128 v[152:155], v156 offset:160
	ds_read_b128 v[156:159], v156 offset:128
	s_waitcnt lgkmcnt(3)
	v_pk_mul_f32 v[12:13], v[12:13], v[144:145]
	s_waitcnt lgkmcnt(2)
	v_pk_mul_f32 v[8:9], v[8:9], v[148:149]
	s_waitcnt lgkmcnt(1)
	v_pk_mul_f32 v[4:5], v[4:5], v[152:153]
	v_pk_mul_f32 v[14:15], v[14:15], v[146:147]
	v_pk_mul_f32 v[10:11], v[10:11], v[150:151]
	v_pk_mul_f32 v[6:7], v[6:7], v[154:155]
	s_waitcnt lgkmcnt(0)
	v_pk_mul_f32 v[2:3], v[2:3], v[158:159]
	v_pk_mul_f32 v[0:1], v[0:1], v[156:157]
	v_pk_mul_f32 v[60:61], v[60:61], v[144:145]
	v_pk_mul_f32 v[56:57], v[56:57], v[148:149]
	v_pk_mul_f32 v[52:53], v[52:53], v[152:153]
	v_pk_mul_f32 v[62:63], v[62:63], v[146:147]
	v_pk_mul_f32 v[58:59], v[58:59], v[150:151]
	v_pk_mul_f32 v[54:55], v[54:55], v[154:155]
	v_pk_mul_f32 v[50:51], v[50:51], v[158:159]
	v_pk_mul_f32 v[48:49], v[48:49], v[156:157]
	v_pk_mul_f32 v[44:45], v[44:45], v[144:145]
	v_pk_mul_f32 v[40:41], v[40:41], v[148:149]
	v_pk_mul_f32 v[36:37], v[36:37], v[152:153]
	v_pk_mul_f32 v[46:47], v[46:47], v[146:147]
	v_pk_mul_f32 v[42:43], v[42:43], v[150:151]
	v_pk_mul_f32 v[38:39], v[38:39], v[154:155]
	v_pk_mul_f32 v[34:35], v[34:35], v[158:159]
	v_pk_mul_f32 v[32:33], v[32:33], v[156:157]
	v_pk_mul_f32 v[28:29], v[28:29], v[144:145]
	v_pk_mul_f32 v[24:25], v[24:25], v[148:149]
	v_pk_mul_f32 v[20:21], v[20:21], v[152:153]
	v_pk_mul_f32 v[30:31], v[30:31], v[146:147]
	v_pk_mul_f32 v[26:27], v[26:27], v[150:151]
	v_pk_mul_f32 v[22:23], v[22:23], v[154:155]
	v_pk_mul_f32 v[18:19], v[18:19], v[158:159]
	v_pk_mul_f32 v[16:17], v[16:17], v[156:157]

; #define SBAR() __builtin_amdgcn_sched_barrier(0)
; #define SLOAD(i, k0) do { sr_[i].vs0 = *(const bf16x8*)(&Vh[(long)((k0) + sr) * LDK + sc]); sr_[i].vs1 = *(const bf16x8*)(&Vh[(long)((k0) + 32 + sr) * LDK + sc]); \
;     sr_[i].ks0 = *(const bf16x8*)(&Kh[(long)((k0) + sr) * LDK + sc]); sr_[i].ks1 = *(const bf16x8*)(&Kh[(long)((k0) + 32 + sr) * LDK + sc]); } while (0)
; #define SWRITE(b, i) do { *(bf16x8*)(V_lds + (b) * SHM_V + vst0) = sr_[i].vs0;          \
;     *(bf16x8*)(V_lds + (b) * SHM_V + vst1) = sr_[i].vs1; int kc = sc * 2;               \
;     *(bf16x8*)(K_lds + (b) * SHM_K + KSWZ(sr, kc)) = sr_[i].ks0;                       \
;     *(bf16x8*)(K_lds + (b) * SHM_K + KSWZ(32 + sr, kc)) = sr_[i].ks1; } while (0)
; #define SWAIT() do { if constexpr (SDEPTH == 2) asm volatile("s_waitcnt vmcnt(4)" ::: "memory"); else asm volatile("s_waitcnt vmcnt(0)" ::: "memory"); } while (0)
; template <int MODE, int SDEPTH, bool SIMPLE>
; __device__ __forceinline__ void attn_body(const Unit& U, char* lds, const int tid) {
;     ...
;     if (SDEPTH == 1 || j + 3 < NT) SLOAD(SE, (j + 1 + SDEPTH) * KVBLK); SBAR();
;     pv_d0(o, vb0 + (int)SHM_V, pa0, pa1, pa2, pa3); partialSM(pA0, pA1, m_reg, mnA, alA);
;     __syncthreads(); SWAIT(); SWRITE(1, SO);
.Lgq_noprefetch:
	s_waitcnt vmcnt(0)
	s_branch .LBB0_205
